# residual f32-path epilogue: xin base loads default policy instead of nt (same flip as v91 did for bf16 path)
# baseline (speedup 1.0000x reference)
; #define PG8_GAS __attribute__((address_space(1)))
; __device__ __forceinline__ unsigned cvtpk(float lo, float hi) { f32x2 v = {lo, hi}; bf16x2_t b = __builtin_convertvector(v, bf16x2_t); return __builtin_bit_cast(unsigned, b); }
; template <class T> __device__ __forceinline__ GAS T* gp(T* p) { return (GAS T*)p; }
;     __device__ __forceinline__ void operator()(const f32x4 (&acc)[2][2][4][2], const Unit& u, int wr, int wc, int fr, int fq) const {
;         const int b = (u.pm * BM) >> 13;
;         const float* gp = mod + b * 9216 + step * 3072 + 2048; const float coef = step == 1 ? 1.0f : 0.5f;
;         const float* basef = step == 0 ? xin : (const float*)nullptr; const bf16_t* baseb = xs; bf16_t* out = xs;
;         const int col0 = u.pn * BM + wc * 32 + 8 * fq;
;         f32x4 gv[2][2];
; #pragma unroll
;         for (int bj = 0; bj < 2; ++bj)
; #pragma unroll
;             for (int n = 0; n < 2; ++n) gv[bj][n] = (*(const PG8_GAS f32x4*)(gp + col0 + bj * HALF + 4 * n) + 1.0f) * coef;
; #pragma unroll
;         for (int ai = 0; ai < 2; ++ai)
; #pragma unroll
;             for (int m = 0; m < 4; ++m) {
;                 const size_t off = (size_t)(u.pm * BM + ai * HALF + wr * 64 + m * 16 + fr) * 1024 + col0;
; #pragma unroll
;                 for (int bj = 0; bj < 2; ++bj) {
;                     f32x4 b0, b1;
;                     if (basef) { b0 = __builtin_nontemporal_load((const PG8_GAS f32x4*)(basef + off + bj * HALF)); b1 = __builtin_nontemporal_load((const PG8_GAS f32x4*)(basef + off + bj * HALF + 4)); }
;                     else { const u32x4 w = __builtin_nontemporal_load((const PG8_GAS u32x4*)(baseb + off + bj * HALF));
;                         b0 = (f32x4){__uint_as_float(w.x << 16), __uint_as_float(w.x & 0xffff0000u), __uint_as_float(w.y << 16), __uint_as_float(w.y & 0xffff0000u)};
;                         b1 = (f32x4){__uint_as_float(w.z << 16), __uint_as_float(w.z & 0xffff0000u), __uint_as_float(w.w << 16), __uint_as_float(w.w & 0xffff0000u)}; }
;                     const f32x4 o0 = b0 + gv[bj][0] * acc[ai][bj][m][0], o1 = b1 + gv[bj][1] * acc[ai][bj][m][1];
;                     u32x4 w; w.x = cvtpk(o0[0], o0[1]); w.y = cvtpk(o0[2], o0[3]); w.z = cvtpk(o1[0], o1[1]); w.w = cvtpk(o1[2], o1[3]);
;                     __builtin_nontemporal_store(w, (PG8_GAS u32x4*)(out + off + bj * HALF));
.LBB0_626:
.LBB0_628:
	s_lshr_b32 s4, s25, 5
	s_mulk_i32 s4, 0x2400
	s_ashr_i32 s5, s4, 31
	s_lshl_b64 s[4:5], s[4:5], 2
	s_add_u32 s4, s38, s4
	v_lshl_or_b32 v2, s40, 8, v178
	s_addc_u32 s5, s18, s5
	v_ashrrev_i32_e32 v3, 31, v2
	v_lshl_add_u64 v[134:135], v[2:3], 2, s[4:5]
	s_mov_b64 s[4:5], 0x2000
	v_lshl_add_u64 v[138:139], v[134:135], 0, s[4:5]
	v_add_co_u32_e32 v134, vcc, s47, v134
	v_add_u32_e32 v170, s42, v176
	s_nop 0
	v_addc_co_u32_e32 v135, vcc, 0, v135, vcc
	global_load_dwordx4 v[146:149], v[134:135], off
	s_nop 0
	global_load_dwordx4 v[134:137], v[138:139], off offset:528
	global_load_dwordx4 v[142:145], v[138:139], off offset:16
	s_nop 0
	global_load_dwordx4 v[138:141], v[138:139], off offset:512
	v_ashrrev_i32_e32 v171, 31, v170
	v_lshlrev_b64 v[150:151], 10, v[170:171]
	v_lshl_add_u64 v[150:151], v[150:151], 0, v[2:3]
	v_lshl_add_u64 v[2:3], v[150:151], 1, s[56:57]
	v_lshl_add_u64 v[174:175], v[150:151], 2, s[64:65]
	v_mov_b64_e32 v[182:183], v[2:3]
	s_andn2_b64 vcc, exec, s[66:67]
	s_cbranch_vccnz .Lres_epi_bf16
	s_mov_b32 s4, 0x10000
	s_mov_b32 s5, 0
	s_mov_b32 vcc_lo, 0x50000
	s_mov_b32 vcc_hi, 0
	global_load_dwordx4 v[150:153], v[174:175], off
	global_load_dwordx4 v[154:157], v[174:175], off offset:16
	global_load_dwordx4 v[170:173], v[174:175], off offset:512
	global_load_dwordx4 v[184:187], v[174:175], off offset:528
	v_lshl_add_u64 v[174:175], v[174:175], 0, s[4:5]
	global_load_dwordx4 v[188:191], v[174:175], off
	global_load_dwordx4 v[192:195], v[174:175], off offset:16
	global_load_dwordx4 v[208:211], v[174:175], off offset:512
	global_load_dwordx4 v[226:229], v[174:175], off offset:528
	v_lshl_add_u64 v[174:175], v[174:175], 0, s[4:5]
	global_load_dwordx4 v[230:233], v[174:175], off
	global_load_dwordx4 v[234:237], v[174:175], off offset:16
	global_load_dwordx4 v[238:241], v[174:175], off offset:512
	global_load_dwordx4 v[242:245], v[174:175], off offset:528
	v_lshl_add_u64 v[174:175], v[174:175], 0, s[4:5]
	global_load_dwordx4 v[246:249], v[174:175], off
	global_load_dwordx4 v[250:253], v[174:175], off offset:16
	s_cmp_eq_u64 s[78:79], 0
	s_cbranch_scc1 .Lres_nb_f32
	s_barrier
.Lres_nb_f32:
	s_waitcnt vmcnt(12)
	v_pk_add_f32 v[148:149], v[148:149], 1.0 op_sel_hi:[1,0]
	v_pk_add_f32 v[180:181], v[146:147], 1.0 op_sel_hi:[1,0]
	v_pk_mul_f32 v[146:147], s[60:61], v[148:149]
	v_pk_mul_f32 v[148:149], s[10:11], v[180:181]
	v_pk_add_f32 v[180:181], v[142:143], 1.0 op_sel_hi:[1,0]
	v_pk_add_f32 v[142:143], v[144:145], 1.0 op_sel_hi:[1,0]
	v_pk_mul_f32 v[144:145], s[10:11], v[180:181]
	v_pk_mul_f32 v[142:143], s[60:61], v[142:143]
	v_pk_add_f32 v[140:141], v[140:141], 1.0 op_sel_hi:[1,0]
	v_pk_add_f32 v[180:181], v[138:139], 1.0 op_sel_hi:[1,0]
	v_pk_mul_f32 v[138:139], s[60:61], v[140:141]
	v_pk_mul_f32 v[140:141], s[10:11], v[180:181]
	v_pk_add_f32 v[180:181], v[134:135], 1.0 op_sel_hi:[1,0]
	v_pk_add_f32 v[134:135], v[136:137], 1.0 op_sel_hi:[1,0]
	v_pk_mul_f32 v[136:137], s[10:11], v[180:181]
	v_pk_mul_f32 v[134:135], s[60:61], v[134:135]
	v_pk_fma_f32 v[130:131], v[130:131], v[148:149], v[150:151]
	v_pk_fma_f32 v[132:133], v[132:133], v[146:147], v[152:153]
	v_pk_fma_f32 v[126:127], v[126:127], v[144:145], v[154:155]
	v_pk_fma_f32 v[128:129], v[128:129], v[142:143], v[156:157]
	v_cvt_pk_bf16_f32 v130, v130, v131
	v_cvt_pk_bf16_f32 v131, v132, v133
	v_cvt_pk_bf16_f32 v132, v126, v127
	v_cvt_pk_bf16_f32 v133, v128, v129
	global_load_dwordx4 v[150:153], v[174:175], off offset:512
	global_load_dwordx4 v[154:157], v[174:175], off offset:528
	v_lshl_add_u64 v[174:175], v[174:175], 0, vcc
	s_waitcnt vmcnt(12)
	v_pk_fma_f32 v[122:123], v[122:123], v[140:141], v[170:171]
	v_pk_fma_f32 v[124:125], v[124:125], v[138:139], v[172:173]
	v_pk_fma_f32 v[118:119], v[118:119], v[136:137], v[184:185]
	v_pk_fma_f32 v[120:121], v[120:121], v[134:135], v[186:187]
	v_cvt_pk_bf16_f32 v122, v122, v123
	v_cvt_pk_bf16_f32 v123, v124, v125
	v_cvt_pk_bf16_f32 v124, v118, v119
	v_cvt_pk_bf16_f32 v125, v120, v121
	global_load_dwordx4 v[126:129], v[174:175], off
	global_load_dwordx4 v[170:173], v[174:175], off offset:16
	global_load_dwordx4 v[184:187], v[174:175], off offset:512
	global_load_dwordx4 v[118:121], v[174:175], off offset:528
	v_lshl_add_u64 v[174:175], v[174:175], 0, s[4:5]
	s_waitcnt vmcnt(14)
	v_pk_fma_f32 v[114:115], v[114:115], v[148:149], v[188:189]
	v_pk_fma_f32 v[116:117], v[116:117], v[146:147], v[190:191]
	v_pk_fma_f32 v[110:111], v[110:111], v[144:145], v[192:193]
	v_pk_fma_f32 v[112:113], v[112:113], v[142:143], v[194:195]
	v_cvt_pk_bf16_f32 v114, v114, v115
	v_cvt_pk_bf16_f32 v115, v116, v117
	v_cvt_pk_bf16_f32 v116, v110, v111
	v_cvt_pk_bf16_f32 v117, v112, v113
	global_load_dwordx4 v[188:191], v[174:175], off
	global_load_dwordx4 v[192:195], v[174:175], off offset:16
	s_waitcnt vmcnt(14)
	v_pk_fma_f32 v[106:107], v[106:107], v[140:141], v[208:209]
	v_pk_fma_f32 v[108:109], v[108:109], v[138:139], v[210:211]
	v_pk_fma_f32 v[102:103], v[102:103], v[136:137], v[226:227]
	v_pk_fma_f32 v[104:105], v[104:105], v[134:135], v[228:229]
	v_cvt_pk_bf16_f32 v106, v106, v107
	v_cvt_pk_bf16_f32 v107, v108, v109
	v_cvt_pk_bf16_f32 v108, v102, v103
	v_cvt_pk_bf16_f32 v109, v104, v105
	global_load_dwordx4 v[110:113], v[174:175], off offset:512
	global_load_dwordx4 v[208:211], v[174:175], off offset:528
	v_lshl_add_u64 v[174:175], v[174:175], 0, s[4:5]
	global_load_dwordx4 v[226:229], v[174:175], off
	global_load_dwordx4 v[102:105], v[174:175], off offset:16
	s_waitcnt vmcnt(16)
; #define PG8_GAS __attribute__((address_space(1)))
; __device__ __forceinline__ unsigned cvtpk(float lo, float hi) { f32x2 v = {lo, hi}; bf16x2_t b = __builtin_convertvector(v, bf16x2_t); return __builtin_bit_cast(unsigned, b); }
;     __device__ __forceinline__ void operator()(const f32x4 (&acc)[2][2][4][2], const Unit& u, int wr, int wc, int fr, int fq) const {
;     ...
;         for (int ai = 0; ai < 2; ++ai)
; #pragma unroll
;             for (int m = 0; m < 4; ++m) {
;                 const size_t off = (size_t)(u.pm * BM + ai * HALF + wr * 64 + m * 16 + fr) * 1024 + col0;
; #pragma unroll
;                 for (int bj = 0; bj < 2; ++bj) {
;                     f32x4 b0, b1;
;                     if (basef) { b0 = __builtin_nontemporal_load((const PG8_GAS f32x4*)(basef + off + bj * HALF)); b1 = __builtin_nontemporal_load((const PG8_GAS f32x4*)(basef + off + bj * HALF + 4)); }
;                     else { const u32x4 w = __builtin_nontemporal_load((const PG8_GAS u32x4*)(baseb + off + bj * HALF));
;                         b0 = (f32x4){__uint_as_float(w.x << 16), __uint_as_float(w.x & 0xffff0000u), __uint_as_float(w.y << 16), __uint_as_float(w.y & 0xffff0000u)};
;                         b1 = (f32x4){__uint_as_float(w.z << 16), __uint_as_float(w.z & 0xffff0000u), __uint_as_float(w.w << 16), __uint_as_float(w.w & 0xffff0000u)}; }
;                     const f32x4 o0 = b0 + gv[bj][0] * acc[ai][bj][m][0], o1 = b1 + gv[bj][1] * acc[ai][bj][m][1];
;                     u32x4 w; w.x = cvtpk(o0[0], o0[1]); w.y = cvtpk(o0[2], o0[3]); w.z = cvtpk(o1[0], o1[1]); w.w = cvtpk(o1[2], o1[3]);
;                     __builtin_nontemporal_store(w, (PG8_GAS u32x4*)(out + off + bj * HALF));
	v_pk_fma_f32 v[98:99], v[98:99], v[148:149], v[230:231]
	v_pk_fma_f32 v[100:101], v[100:101], v[146:147], v[232:233]
	v_pk_fma_f32 v[94:95], v[94:95], v[144:145], v[234:235]
	v_pk_fma_f32 v[96:97], v[96:97], v[142:143], v[236:237]
	v_cvt_pk_bf16_f32 v98, v98, v99
	v_cvt_pk_bf16_f32 v99, v100, v101
	v_cvt_pk_bf16_f32 v100, v94, v95
	v_cvt_pk_bf16_f32 v101, v96, v97
	global_load_dwordx4 v[230:233], v[174:175], off offset:512
	global_load_dwordx4 v[234:237], v[174:175], off offset:528
	v_lshl_add_u64 v[174:175], v[174:175], 0, s[4:5]
	s_waitcnt vmcnt(16)
	v_pk_fma_f32 v[90:91], v[90:91], v[140:141], v[238:239]
	v_pk_fma_f32 v[92:93], v[92:93], v[138:139], v[240:241]
	v_pk_fma_f32 v[86:87], v[86:87], v[136:137], v[242:243]
	v_pk_fma_f32 v[88:89], v[88:89], v[134:135], v[244:245]
	v_cvt_pk_bf16_f32 v90, v90, v91
	v_cvt_pk_bf16_f32 v91, v92, v93
	v_cvt_pk_bf16_f32 v92, v86, v87
	v_cvt_pk_bf16_f32 v93, v88, v89
	global_load_dwordx4 v[94:97], v[174:175], off
	global_load_dwordx4 v[238:241], v[174:175], off offset:16
	global_load_dwordx4 v[242:245], v[174:175], off offset:512
	global_load_dwordx4 v[86:89], v[174:175], off offset:528
	s_mov_b32 s4, 0x8000
	s_mov_b32 vcc_lo, 0x28000
	global_store_dwordx4 v[2:3], v[130:133], off
	global_store_dwordx4 v[2:3], v[122:125], off offset:256
	v_lshl_add_u64 v[2:3], v[2:3], 0, s[4:5]
	global_store_dwordx4 v[2:3], v[114:117], off
	global_store_dwordx4 v[2:3], v[106:109], off offset:256
	v_lshl_add_u64 v[2:3], v[2:3], 0, s[4:5]
	global_store_dwordx4 v[2:3], v[98:101], off
	global_store_dwordx4 v[2:3], v[90:93], off offset:256
	v_lshl_add_u64 v[2:3], v[2:3], 0, s[4:5]
	s_waitcnt vmcnt(24)
	v_pk_fma_f32 v[82:83], v[82:83], v[148:149], v[246:247]
	v_pk_fma_f32 v[84:85], v[84:85], v[146:147], v[248:249]
	v_pk_fma_f32 v[78:79], v[78:79], v[144:145], v[250:251]
	v_pk_fma_f32 v[80:81], v[80:81], v[142:143], v[252:253]
	v_cvt_pk_bf16_f32 v82, v82, v83
	v_cvt_pk_bf16_f32 v83, v84, v85
	v_cvt_pk_bf16_f32 v84, v78, v79
	v_cvt_pk_bf16_f32 v85, v80, v81
	global_store_dwordx4 v[2:3], v[82:85], off
	s_waitcnt vmcnt(23)
	v_pk_fma_f32 v[74:75], v[74:75], v[140:141], v[150:151]
	v_pk_fma_f32 v[76:77], v[76:77], v[138:139], v[152:153]
	v_pk_fma_f32 v[70:71], v[70:71], v[136:137], v[154:155]
	v_pk_fma_f32 v[72:73], v[72:73], v[134:135], v[156:157]
	v_cvt_pk_bf16_f32 v74, v74, v75
	v_cvt_pk_bf16_f32 v75, v76, v77
	v_cvt_pk_bf16_f32 v76, v70, v71
	v_cvt_pk_bf16_f32 v77, v72, v73
	global_store_dwordx4 v[2:3], v[74:77], off offset:256
	v_lshl_add_u64 v[2:3], v[2:3], 0, vcc
	s_waitcnt vmcnt(22)
	v_pk_fma_f32 v[66:67], v[66:67], v[148:149], v[126:127]
	v_pk_fma_f32 v[68:69], v[68:69], v[146:147], v[128:129]
	v_pk_fma_f32 v[62:63], v[62:63], v[144:145], v[170:171]
	v_pk_fma_f32 v[64:65], v[64:65], v[142:143], v[172:173]
	v_cvt_pk_bf16_f32 v66, v66, v67
	v_cvt_pk_bf16_f32 v67, v68, v69
	v_cvt_pk_bf16_f32 v68, v62, v63
	v_cvt_pk_bf16_f32 v69, v64, v65
	global_store_dwordx4 v[2:3], v[66:69], off
	s_waitcnt vmcnt(21)
	v_pk_fma_f32 v[58:59], v[58:59], v[140:141], v[184:185]
	v_pk_fma_f32 v[60:61], v[60:61], v[138:139], v[186:187]
	v_pk_fma_f32 v[54:55], v[54:55], v[136:137], v[118:119]
	v_pk_fma_f32 v[56:57], v[56:57], v[134:135], v[120:121]
	v_cvt_pk_bf16_f32 v58, v58, v59
	v_cvt_pk_bf16_f32 v59, v60, v61
	v_cvt_pk_bf16_f32 v60, v54, v55
	v_cvt_pk_bf16_f32 v61, v56, v57
	global_store_dwordx4 v[2:3], v[58:61], off offset:256
	v_lshl_add_u64 v[2:3], v[2:3], 0, s[4:5]
	s_waitcnt vmcnt(20)
	v_pk_fma_f32 v[50:51], v[50:51], v[148:149], v[188:189]
	v_pk_fma_f32 v[52:53], v[52:53], v[146:147], v[190:191]
	v_pk_fma_f32 v[46:47], v[46:47], v[144:145], v[192:193]
	v_pk_fma_f32 v[48:49], v[48:49], v[142:143], v[194:195]
	v_cvt_pk_bf16_f32 v50, v50, v51
	v_cvt_pk_bf16_f32 v51, v52, v53
	v_cvt_pk_bf16_f32 v52, v46, v47
	v_cvt_pk_bf16_f32 v53, v48, v49
	global_store_dwordx4 v[2:3], v[50:53], off
	s_waitcnt vmcnt(19)
	v_pk_fma_f32 v[42:43], v[42:43], v[140:141], v[110:111]
	v_pk_fma_f32 v[44:45], v[44:45], v[138:139], v[112:113]
	v_pk_fma_f32 v[38:39], v[38:39], v[136:137], v[208:209]
	v_pk_fma_f32 v[40:41], v[40:41], v[134:135], v[210:211]
	v_cvt_pk_bf16_f32 v42, v42, v43
	v_cvt_pk_bf16_f32 v43, v44, v45
	v_cvt_pk_bf16_f32 v44, v38, v39
	v_cvt_pk_bf16_f32 v45, v40, v41
	global_store_dwordx4 v[2:3], v[42:45], off offset:256
	v_lshl_add_u64 v[2:3], v[2:3], 0, s[4:5]
	s_waitcnt vmcnt(18)
	v_pk_fma_f32 v[34:35], v[34:35], v[148:149], v[226:227]
	v_pk_fma_f32 v[36:37], v[36:37], v[146:147], v[228:229]
	v_pk_fma_f32 v[30:31], v[30:31], v[144:145], v[102:103]
	v_pk_fma_f32 v[32:33], v[32:33], v[142:143], v[104:105]
	v_cvt_pk_bf16_f32 v34, v34, v35
	v_cvt_pk_bf16_f32 v35, v36, v37
	v_cvt_pk_bf16_f32 v36, v30, v31
	v_cvt_pk_bf16_f32 v37, v32, v33
	global_store_dwordx4 v[2:3], v[34:37], off
	s_waitcnt vmcnt(17)
	v_pk_fma_f32 v[26:27], v[26:27], v[140:141], v[230:231]
	v_pk_fma_f32 v[28:29], v[28:29], v[138:139], v[232:233]
	v_pk_fma_f32 v[22:23], v[22:23], v[136:137], v[234:235]
	v_pk_fma_f32 v[24:25], v[24:25], v[134:135], v[236:237]
	v_cvt_pk_bf16_f32 v26, v26, v27
	v_cvt_pk_bf16_f32 v27, v28, v29
	v_cvt_pk_bf16_f32 v28, v22, v23
	v_cvt_pk_bf16_f32 v29, v24, v25
	global_store_dwordx4 v[2:3], v[26:29], off offset:256
	v_lshl_add_u64 v[2:3], v[2:3], 0, s[4:5]
	s_waitcnt vmcnt(16)
	v_pk_fma_f32 v[18:19], v[18:19], v[148:149], v[94:95]
	v_pk_fma_f32 v[20:21], v[20:21], v[146:147], v[96:97]
	v_pk_fma_f32 v[14:15], v[14:15], v[144:145], v[238:239]
	v_pk_fma_f32 v[16:17], v[16:17], v[142:143], v[240:241]
	v_cvt_pk_bf16_f32 v18, v18, v19
	v_cvt_pk_bf16_f32 v19, v20, v21
	v_cvt_pk_bf16_f32 v20, v14, v15
	v_cvt_pk_bf16_f32 v21, v16, v17
	global_store_dwordx4 v[2:3], v[18:21], off
	s_waitcnt vmcnt(15)
	v_pk_fma_f32 v[10:11], v[10:11], v[140:141], v[242:243]
	v_pk_fma_f32 v[12:13], v[12:13], v[138:139], v[244:245]
	v_pk_fma_f32 v[6:7], v[6:7], v[136:137], v[86:87]
	v_pk_fma_f32 v[8:9], v[8:9], v[134:135], v[88:89]
	v_cvt_pk_bf16_f32 v10, v10, v11
	v_cvt_pk_bf16_f32 v11, v12, v13
	v_cvt_pk_bf16_f32 v12, v6, v7
	v_cvt_pk_bf16_f32 v13, v8, v9
	s_and_b64 vcc, exec, s[6:7]
	s_mov_b64 s[4:5], -1
	global_store_dwordx4 v[2:3], v[10:13], off offset:256
	s_branch .Lres_epi_tail
